# attention item mapping: the 32 workgroups of an XCD take 32 consecutive query blocks at the same time (neighbour K/V tile overlap served by L2) instead of 4 consecutive blocks per workgroup
# speedup vs baseline: 1.0000x; 1.0000x over previous
.LBB0_1117:
	s_cmp_le_i32 s79, s22
	s_cselect_b64 s[0:1], -1, 0
	s_and_b64 s[4:5], s[0:1], s[4:5]
	s_andn2_b64 vcc, exec, s[4:5]
	s_cbranch_vccnz .LBB0_1428
	s_mov_b64 s[8:9], s[92:93]
	v_writelane_b32 v254, s4, 41
	s_load_dwordx2 s[0:1], s[8:9], 0x70
	v_mbcnt_lo_u32_b32 v0, -1, 0
	v_mbcnt_hi_u32_b32 v0, -1, v0
	v_readlane_b32 s6, v253, 2
	v_writelane_b32 v254, s5, 42
	v_writelane_b32 v254, s26, 43
	v_add_u32_e32 v148, s37, v0
	s_movk_i32 s67, 0x81
	v_writelane_b32 v254, s27, 44
	v_writelane_b32 v254, s96, 45
	s_waitcnt lgkmcnt(0)
	v_writelane_b32 v254, s0, 46
	v_mov_b32_e32 v19, v148
	s_nop 0
	v_writelane_b32 v254, s1, 47
	v_writelane_b32 v254, s95, 48
	s_cmp_lg_u32 s95, 3
	s_cselect_b64 s[0:1], -1, 0
	v_writelane_b32 v254, s0, 49
	s_cmp_lt_i32 s95, 2
	s_nop 0
	v_writelane_b32 v254, s1, 50
	s_cselect_b64 s[0:1], -1, 0
	s_and_b64 s[4:5], s[0:1], exec
	s_cselect_b32 s53, 11, 10
	s_add_i32 s5, s53, -10
	s_lshl_b32 s5, s6, s5
	s_lshl_b32 s4, 1, s53
	s_and_b32 s58, s2, 7
	s_lshl_b32 s59, s5, 5
	s_mul_i32 s58, s58, s59
	s_lshr_b32 s98, s2, 3
	s_add_i32 s58, s58, s98
	s_add_i32 s59, s58, s59
	s_lshr_b32 s4, s4, 1
	v_writelane_b32 v254, s95, 51
	s_cmp_ge_i32 s58, s59
	s_cbranch_scc1 .LBB0_1245
	v_readlane_b32 s28, v254, 51
	s_min_i32 s12, s28, 2
	s_load_dwordx2 s[6:7], s[8:9], 0x70
	s_lshl_b32 s40, s12, 1
	s_lshr_b32 s41, 0x4000, s40
	s_and_b64 s[4:5], s[0:1], exec
	s_brev_b32 s4, 64
	s_cselect_b32 s4, s4, 0x1000000
	s_waitcnt lgkmcnt(0)
	s_add_u32 s6, s6, 0x4000000
	s_addc_u32 s7, s7, 0
	s_lshl_b32 s13, s4, 1
	s_add_u32 s4, s6, s13
	s_addc_u32 s5, s7, 0
	s_sub_i32 s62, 6, s40
	s_and_b32 s11, s58, 63
	s_lshl_b32 s14, -1, s62
	s_andn2_b32 s18, s11, s14
	s_ashr_i32 s10, s58, 6
	s_lshr_b32 s15, s11, s62
	s_lshl_b32 s11, s18, 8
	s_add_i32 s19, s11, 0xffffff80
	s_ashr_i32 s11, s10, 31
	s_lshl_b64 s[10:11], s[10:11], 14
	s_mul_i32 s15, s15, s41
	s_ashr_i32 s20, s19, 31
	s_add_u32 s15, s19, s15
	s_addc_u32 s19, s20, 0
	v_ashrrev_i32_e32 v128, 4, v19
	s_add_u32 s10, s15, s10
	v_ashrrev_i32_e32 v129, 31, v128
	s_addc_u32 s11, s19, s11
	v_lshl_add_u64 v[0:1], s[10:11], 0, v[128:129]
	v_and_b32_e32 v18, 15, v19
	v_lshlrev_b64 v[0:1], 8, v[0:1]
	v_lshl_add_u64 v[0:1], s[4:5], 0, v[0:1]
	v_lshlrev_b32_e32 v138, 4, v18
	s_cmp_lg_u32 s18, 0
	s_cselect_b64 s[10:11], -1, 0
	s_cmp_eq_u32 s18, 0
	v_lshl_add_u64 v[16:17], v[0:1], 0, v[138:139]
	s_waitcnt vmcnt(0)
	s_barrier
	s_cbranch_scc1 .LBB0_1121
	global_load_dwordx4 v[0:3], v[16:17], off
	s_branch .LBB0_1122

.LBB0_1196:
	v_pk_mul_f32 v[48:49], v[140:141], v[48:49] op_sel_hi:[0,1]
	v_pk_mul_f32 v[50:51], v[140:141], v[50:51] op_sel_hi:[0,1]
	v_pk_mul_f32 v[32:33], v[140:141], v[32:33] op_sel_hi:[0,1]
	v_pk_mul_f32 v[34:35], v[140:141], v[34:35] op_sel_hi:[0,1]
	v_pk_mul_f32 v[16:17], v[140:141], v[16:17] op_sel_hi:[0,1]
	v_pk_mul_f32 v[18:19], v[140:141], v[18:19] op_sel_hi:[0,1]
	v_pk_mul_f32 v[0:1], v[140:141], v[0:1] op_sel_hi:[0,1]
	v_pk_mul_f32 v[2:3], v[140:141], v[2:3] op_sel_hi:[0,1]
	s_barrier
	ds_write_b128 v162, v[48:51]
	v_pk_mul_f32 v[48:49], v[140:141], v[52:53] op_sel_hi:[0,1]
	v_pk_mul_f32 v[50:51], v[140:141], v[54:55] op_sel_hi:[0,1]
	ds_write_b128 v162, v[32:35] offset:128
	v_pk_mul_f32 v[32:33], v[140:141], v[36:37] op_sel_hi:[0,1]
	v_pk_mul_f32 v[34:35], v[140:141], v[38:39] op_sel_hi:[0,1]
	ds_write_b128 v162, v[16:19] offset:256
	v_pk_mul_f32 v[16:17], v[140:141], v[20:21] op_sel_hi:[0,1]
	v_pk_mul_f32 v[18:19], v[140:141], v[22:23] op_sel_hi:[0,1]
	ds_write_b128 v162, v[0:3] offset:384
	v_pk_mul_f32 v[0:1], v[140:141], v[4:5] op_sel_hi:[0,1]
	v_pk_mul_f32 v[2:3], v[140:141], v[6:7] op_sel_hi:[0,1]
	ds_write_b128 v162, v[48:51] offset:32
	v_pk_mul_f32 v[48:49], v[140:141], v[56:57] op_sel_hi:[0,1]
	v_pk_mul_f32 v[50:51], v[140:141], v[58:59] op_sel_hi:[0,1]
	ds_write_b128 v162, v[32:35] offset:160
	v_pk_mul_f32 v[32:33], v[140:141], v[40:41] op_sel_hi:[0,1]
	v_pk_mul_f32 v[34:35], v[140:141], v[42:43] op_sel_hi:[0,1]
	ds_write_b128 v162, v[16:19] offset:288
	v_pk_mul_f32 v[16:17], v[140:141], v[24:25] op_sel_hi:[0,1]
	v_pk_mul_f32 v[18:19], v[140:141], v[26:27] op_sel_hi:[0,1]
	ds_write_b128 v162, v[0:3] offset:416
	v_pk_mul_f32 v[0:1], v[140:141], v[8:9] op_sel_hi:[0,1]
	v_pk_mul_f32 v[2:3], v[140:141], v[10:11] op_sel_hi:[0,1]
	ds_write_b128 v162, v[48:51] offset:64
	v_pk_mul_f32 v[48:49], v[140:141], v[60:61] op_sel_hi:[0,1]
	v_pk_mul_f32 v[50:51], v[140:141], v[62:63] op_sel_hi:[0,1]
	ds_write_b128 v162, v[32:35] offset:192
	v_pk_mul_f32 v[32:33], v[140:141], v[44:45] op_sel_hi:[0,1]
	v_pk_mul_f32 v[34:35], v[140:141], v[46:47] op_sel_hi:[0,1]
	ds_write_b128 v162, v[16:19] offset:320
	v_pk_mul_f32 v[16:17], v[140:141], v[28:29] op_sel_hi:[0,1]
	v_pk_mul_f32 v[18:19], v[140:141], v[30:31] op_sel_hi:[0,1]
	ds_write_b128 v162, v[0:3] offset:448
	v_pk_mul_f32 v[0:1], v[140:141], v[12:13] op_sel_hi:[0,1]
	v_pk_mul_f32 v[2:3], v[140:141], v[14:15] op_sel_hi:[0,1]
	ds_write_b128 v162, v[48:51] offset:96
	ds_write_b128 v162, v[32:35] offset:224
	ds_write_b128 v162, v[16:19] offset:352
	ds_write_b128 v162, v[0:3] offset:480
	s_and_saveexec_b64 s[12:13], s[42:43]
	ds_write_b32 v160, v144
	s_or_b64 exec, exec, s[12:13]
	s_waitcnt lgkmcnt(0)
	s_add_i32 s58, s58, 32
	s_cmp_lt_i32 s58, s59
	v_mov_b32_e32 v3, 0
	s_cselect_b64 s[94:95], -1, 0
	s_cmp_ge_i32 s58, s59
	v_mov_b32_e32 v2, 0
	v_mov_b32_e32 v1, 0
	v_mov_b32_e32 v0, 0
	v_mov_b32_e32 v11, 0
	v_mov_b32_e32 v10, 0
	v_mov_b32_e32 v9, 0
	v_mov_b32_e32 v8, 0
	v_mov_b32_e32 v7, 0
	v_mov_b32_e32 v6, 0
	v_mov_b32_e32 v5, 0
	v_mov_b32_e32 v4, 0
	v_mov_b32_e32 v15, 0
	v_mov_b32_e32 v14, 0
	v_mov_b32_e32 v13, 0
	v_mov_b32_e32 v12, 0
	v_mov_b32_e32 v19, 0
	v_mov_b32_e32 v18, 0
	v_mov_b32_e32 v17, 0
	v_mov_b32_e32 v16, 0
	v_mov_b32_e32 v23, 0
	v_mov_b32_e32 v22, 0
	v_mov_b32_e32 v21, 0
	v_mov_b32_e32 v20, 0
	v_mov_b32_e32 v27, 0
	v_mov_b32_e32 v26, 0
	v_mov_b32_e32 v25, 0
	v_mov_b32_e32 v24, 0
	v_mov_b32_e32 v31, 0
	v_mov_b32_e32 v30, 0
	v_mov_b32_e32 v29, 0
	v_mov_b32_e32 v28, 0
	v_mov_b32_e32 v35, 0
	v_mov_b32_e32 v34, 0
	v_mov_b32_e32 v33, 0
	v_mov_b32_e32 v32, 0
	v_mov_b32_e32 v39, 0
	v_mov_b32_e32 v38, 0
	v_mov_b32_e32 v37, 0
	v_mov_b32_e32 v36, 0
	v_mov_b32_e32 v43, 0
	v_mov_b32_e32 v42, 0
	v_mov_b32_e32 v41, 0
	v_mov_b32_e32 v40, 0
	v_mov_b32_e32 v47, 0
	v_mov_b32_e32 v46, 0
	v_mov_b32_e32 v45, 0
	v_mov_b32_e32 v44, 0
	s_cbranch_scc1 .LBB0_1211
	s_and_b32 s5, s58, 63
	s_and_b32 s14, s5, s63
	s_ashr_i32 s4, s58, 6
	s_lshr_b32 s12, s5, s62
	s_lshl_b32 s5, s14, 8
	s_add_i32 s13, s5, 0xffffff80
	s_ashr_i32 s5, s4, 31
	s_lshl_b64 s[4:5], s[4:5], 14
	s_mul_i32 s12, s12, s41
	s_ashr_i32 s15, s13, 31
	s_add_u32 s12, s13, s12
	s_addc_u32 s13, s15, 0
	s_add_u32 s4, s12, s4
	s_addc_u32 s5, s13, s5
	v_lshl_add_u64 v[0:1], s[4:5], 0, v[128:129]
	v_lshlrev_b64 v[0:1], 8, v[0:1]
	s_cmp_lg_u32 s14, 0
	s_cselect_b64 s[12:13], -1, 0
	s_cmp_eq_u32 s14, 0
	v_lshl_add_u64 v[40:41], v[136:137], 0, v[0:1]
	s_cbranch_scc1 .LBB0_1202
	global_load_dwordx4 v[0:3], v[40:41], off
	s_branch .LBB0_1203
